# v19 + tile_max cross-half exchange via v_permlane32_swap instead of ds_bpermute (fox, NSA loops)
# baseline (speedup 1.0000x reference)
; DI float ex2(float x) { return __builtin_amdgcn_exp2f(x); }
; DI float tile_max(const f32x16& x0, const f32x16& x1) {
;     float ma = __builtin_fmaxf(x0[0], x1[0]), mb = __builtin_fmaxf(x0[1], x1[1]);
; #pragma unroll
;     for (int i = 2; i < 16; i += 2) { ma = __builtin_fmaxf(__builtin_fmaxf(ma, x0[i]), x1[i]); mb = __builtin_fmaxf(__builtin_fmaxf(mb, x0[i + 1]), x1[i + 1]); }
;     const float mx = __builtin_fmaxf(ma, mb);
;     return __builtin_fmaxf(mx, __shfl_xor(mx, 32));
; }
; DI void smx_tile(f32x16& x0, f32x16& x1, float& m, float& l, f32x16& o0, f32x16& o1) {
;     const float mn = fmaxf(m, tile_max(x0, x1) * C2);
;     const float al = ex2(m - mn); m = mn; l *= al;
;     if (__any(al != 1.f)) {
; #pragma unroll
;         for (int i = 0; i < 16; ++i) { o0[i] *= al; o1[i] *= al; }
;     }
.LBB0_354:
	s_nop 10
	v_max_f32_e32 v0, v35, v35
	v_max_f32_e32 v85, v51, v51
	v_max_f32_e32 v0, v85, v0
	v_max3_f32 v85, v50, v34, v52
	v_max3_f32 v0, v0, v53, v37
	v_max3_f32 v85, v85, v36, v54
	v_max3_f32 v0, v0, v55, v39
	v_max3_f32 v85, v85, v38, v56
	v_max3_f32 v0, v0, v57, v41
	v_max3_f32 v85, v85, v40, v58
	v_max3_f32 v0, v0, v59, v43
	v_max3_f32 v85, v85, v42, v60
	v_max3_f32 v0, v0, v61, v45
	v_max3_f32 v85, v85, v44, v62
	v_max3_f32 v0, v0, v63, v47
	v_max3_f32 v85, v85, v46, v64
	v_max3_f32 v0, v0, v65, v49
	v_max3_f32 v0, v85, v48, v0
	v_mov_b32_e32 v85, v0
	v_mov_b32_e32 v251, v0
	s_nop 1
	v_permlane32_swap_b32_e32 v85, v251
	s_waitcnt lgkmcnt(0)
	v_max_f32_e32 v85, v85, v251
	v_max_f32_e32 v0, v0, v85
	v_mul_f32_e32 v0, 0x3e38aa3b, v0
	v_max_f32_e32 v85, v237, v237
	v_max_f32_e32 v85, v85, v0
	v_sub_f32_e32 v0, v237, v85
	v_exp_f32_e32 v160, v0
	s_nop 0
	v_cmp_neq_f32_e32 vcc, 1.0, v160
	s_cbranch_vccz .LBB0_356
	v_pk_mul_f32 v[32:33], v[32:33], v[160:161] op_sel_hi:[1,0]
	v_pk_mul_f32 v[30:31], v[30:31], v[160:161] op_sel_hi:[1,0]
	v_pk_mul_f32 v[28:29], v[28:29], v[160:161] op_sel_hi:[1,0]
	v_pk_mul_f32 v[26:27], v[26:27], v[160:161] op_sel_hi:[1,0]
	v_pk_mul_f32 v[24:25], v[24:25], v[160:161] op_sel_hi:[1,0]
	v_pk_mul_f32 v[22:23], v[22:23], v[160:161] op_sel_hi:[1,0]
	v_pk_mul_f32 v[20:21], v[20:21], v[160:161] op_sel_hi:[1,0]
	v_pk_mul_f32 v[18:19], v[18:19], v[160:161] op_sel_hi:[1,0]
	v_pk_mul_f32 v[16:17], v[16:17], v[160:161] op_sel_hi:[1,0]
	v_pk_mul_f32 v[14:15], v[14:15], v[160:161] op_sel_hi:[1,0]
	v_pk_mul_f32 v[12:13], v[12:13], v[160:161] op_sel_hi:[1,0]
	v_pk_mul_f32 v[10:11], v[10:11], v[160:161] op_sel_hi:[1,0]
	v_pk_mul_f32 v[8:9], v[8:9], v[160:161] op_sel_hi:[1,0]
	v_pk_mul_f32 v[6:7], v[6:7], v[160:161] op_sel_hi:[1,0]
	v_pk_mul_f32 v[4:5], v[4:5], v[160:161] op_sel_hi:[1,0]
	v_pk_mul_f32 v[2:3], v[2:3], v[160:161] op_sel_hi:[1,0]

; DI float ex2(float x) { return __builtin_amdgcn_exp2f(x); }
; DI float tile_max(const f32x16& x0, const f32x16& x1) {
;     float ma = __builtin_fmaxf(x0[0], x1[0]), mb = __builtin_fmaxf(x0[1], x1[1]);
; #pragma unroll
;     for (int i = 2; i < 16; i += 2) { ma = __builtin_fmaxf(__builtin_fmaxf(ma, x0[i]), x1[i]); mb = __builtin_fmaxf(__builtin_fmaxf(mb, x0[i + 1]), x1[i + 1]); }
;     const float mx = __builtin_fmaxf(ma, mb);
;     return __builtin_fmaxf(mx, __shfl_xor(mx, 32));
; }
; DI void smx_tile(f32x16& x0, f32x16& x1, float& m, float& l, f32x16& o0, f32x16& o1) {
;     const float mn = fmaxf(m, tile_max(x0, x1) * C2);
;     const float al = ex2(m - mn); m = mn; l *= al;
;     if (__any(al != 1.f)) {
; #pragma unroll
;         for (int i = 0; i < 16; ++i) { o0[i] *= al; o1[i] *= al; }
;     }
.LBB0_398:
	s_nop 10
	v_max_f32_e32 v0, v37, v37
	v_max_f32_e32 v111, v53, v53
	v_max_f32_e32 v0, v111, v0
	v_max3_f32 v111, v52, v36, v54
	v_max3_f32 v0, v0, v55, v39
	v_max3_f32 v111, v111, v38, v56
	v_max3_f32 v0, v0, v57, v41
	v_max3_f32 v111, v111, v40, v58
	v_max3_f32 v0, v0, v59, v43
	v_max3_f32 v111, v111, v42, v60
	v_max3_f32 v0, v0, v61, v45
	v_max3_f32 v111, v111, v44, v62
	v_max3_f32 v0, v0, v63, v47
	v_max3_f32 v111, v111, v46, v64
	v_max3_f32 v0, v0, v65, v49
	v_max3_f32 v111, v111, v48, v66
	v_max3_f32 v0, v0, v67, v51
	v_max3_f32 v0, v111, v50, v0
	v_mov_b32_e32 v111, v0
	v_mov_b32_e32 v251, v0
	s_nop 1
	v_permlane32_swap_b32_e32 v111, v251
	s_waitcnt lgkmcnt(0)
	v_max_f32_e32 v111, v111, v251
	v_max_f32_e32 v0, v0, v111
	v_mul_f32_e32 v0, 0x3e38aa3b, v0
	v_max_f32_e32 v111, v237, v237
	v_max_f32_e32 v111, v111, v0
	v_sub_f32_e32 v0, v237, v111
	v_exp_f32_e32 v162, v0
	s_nop 0
	v_cmp_neq_f32_e32 vcc, 1.0, v162
	s_cbranch_vccz .LBB0_400
	v_pk_mul_f32 v[32:33], v[32:33], v[162:163] op_sel_hi:[1,0]
	v_pk_mul_f32 v[30:31], v[30:31], v[162:163] op_sel_hi:[1,0]
	v_pk_mul_f32 v[28:29], v[28:29], v[162:163] op_sel_hi:[1,0]
	v_pk_mul_f32 v[26:27], v[26:27], v[162:163] op_sel_hi:[1,0]
	v_pk_mul_f32 v[24:25], v[24:25], v[162:163] op_sel_hi:[1,0]
	v_pk_mul_f32 v[22:23], v[22:23], v[162:163] op_sel_hi:[1,0]
	v_pk_mul_f32 v[20:21], v[20:21], v[162:163] op_sel_hi:[1,0]
	v_pk_mul_f32 v[18:19], v[18:19], v[162:163] op_sel_hi:[1,0]
	v_pk_mul_f32 v[16:17], v[16:17], v[162:163] op_sel_hi:[1,0]
	v_pk_mul_f32 v[14:15], v[14:15], v[162:163] op_sel_hi:[1,0]
	v_pk_mul_f32 v[12:13], v[12:13], v[162:163] op_sel_hi:[1,0]
	v_pk_mul_f32 v[10:11], v[10:11], v[162:163] op_sel_hi:[1,0]
	v_pk_mul_f32 v[8:9], v[8:9], v[162:163] op_sel_hi:[1,0]
	v_pk_mul_f32 v[6:7], v[6:7], v[162:163] op_sel_hi:[1,0]
	v_pk_mul_f32 v[4:5], v[4:5], v[162:163] op_sel_hi:[1,0]
	v_pk_mul_f32 v[2:3], v[2:3], v[162:163] op_sel_hi:[1,0]

; DI void qk_tile(const char* kb, const bf16x8 (&qr)[5], int r32, int hi, f32x16& x0, f32x16& x1) {
;     bf16x8 kf[10];
; #pragma unroll
;     for (int d0 = 0; d0 < 4; ++d0) {
;         kf[2 * d0] = *(const bf16x8*)(kb + (2 * d0 + hi) * 1024 + r32 * 16);
;         kf[2 * d0 + 1] = *(const bf16x8*)(kb + (2 * d0 + hi) * 1024 + 512 + r32 * 16);
;     }
;     kf[8] = *(const bf16x8*)(kb + 8192 + r32 * 16);
;     kf[9] = *(const bf16x8*)(kb + 8192 + 512 + r32 * 16);
;     asm volatile("s_waitcnt lgkmcnt(0)" ::: "memory");
; #pragma unroll
;     for (int i = 0; i < 16; ++i) { x0[i] = 0.f; x1[i] = 0.f; }
; #pragma unroll
;     for (int d0 = 0; d0 < 5; ++d0) { x0 = MFMA32(kf[2 * d0], qr[d0], x0); x1 = MFMA32(kf[2 * d0 + 1], qr[d0], x1); }
; }
; DI void v_load(const char* vb, int lane, int hi, bf16x8 (&vf)[8]) {
;     const lds_cptr vp = (lds_cptr)vb + ((lane >> 4) & 1) * 32 + (lane & 3) * 8 + (4 * hi + ((lane & 15) >> 2)) * 64;
; #pragma unroll
;     for (int ks = 0; ks < 4; ++ks) {
;         { const s16x4 lo = vtr(vp + ks * 1024), hh = vtr(vp + ks * 1024 + 512); vf[ks] = (bf16x8){lo[0], lo[1], lo[2], lo[3], hh[0], hh[1], hh[2], hh[3]}; }
;         { const s16x4 lo = vtr(vp + 4096 + ks * 1024), hh = vtr(vp + 4096 + ks * 1024 + 512); vf[4 + ks] = (bf16x8){lo[0], lo[1], lo[2], lo[3], hh[0], hh[1], hh[2], hh[3]}; }
;     }
;     asm volatile("" ::: "memory");
; }
; DI void pv_tile(const bf16x8 (&vf)[8], const f32x16& p0, const f32x16& p1, f32x16& o0, f32x16& o1) {
;     u32x4 w[4];
; #pragma unroll
;     for (int j = 0; j < 4; ++j) { w[0][j] = cvtpk(p0[2 * j], p0[2 * j + 1]); w[1][j] = cvtpk(p0[8 + 2 * j], p0[9 + 2 * j]);
;                                   w[2][j] = cvtpk(p1[2 * j], p1[2 * j + 1]); w[3][j] = cvtpk(p1[8 + 2 * j], p1[9 + 2 * j]); }
; #pragma unroll
;     for (int ks = 0; ks < 4; ++ks) { const bf16x8 pb = __builtin_bit_cast(bf16x8, w[ks]); o0 = MFMA32(vf[ks], pb, o0); o1 = MFMA32(vf[4 + ks], pb, o1); }
; }
; DI void mask_tile(f32x16& x0, f32x16& x1, int klo, int khi, int hi) {
; #pragma unroll
;     for (int i = 0; i < 16; ++i) { const int k = crow(i, hi); if (k < klo || k > khi) x0[i] = NEGX; if (k + 32 < klo || k + 32 > khi) x1[i] = NEGX; }
; }
; DI float tile_max(const f32x16& x0, const f32x16& x1) {
;     float ma = __builtin_fmaxf(x0[0], x1[0]), mb = __builtin_fmaxf(x0[1], x1[1]);
; #pragma unroll
.LBB0_488:
	v_add_u32_e32 v44, v34, v166
	ds_read_b128 v[2:5], v44
	ds_read_b128 v[18:21], v44 offset:512
	ds_read_b128 v[36:39], v44 offset:2048
	ds_read_b128 v[40:43], v44 offset:2560
	v_and_b32_e32 v46, 64, v181
	v_xor_b32_e32 v45, 32, v181
	s_waitcnt lgkmcnt(3)
	v_mfma_f32_32x32x16_bf16 v[2:17], v[2:5], v[68:71], 0
	v_add_u32_e32 v133, 64, v46
	v_cmp_lt_i32_e32 vcc, v45, v133
	v_cmp_lt_i32_e64 s[6:7], v167, v35
	v_cmp_le_i32_e64 s[8:9], v169, v35
	v_cmp_le_i32_e64 s[0:1], v168, v35
	v_cmp_le_i32_e64 s[14:15], v170, v35
	v_cmp_le_i32_e64 s[18:19], v186, v35
	s_waitcnt lgkmcnt(2)
	v_mfma_f32_32x32x16_bf16 v[18:33], v[18:21], v[68:71], 0
	v_cmp_le_i32_e64 s[20:21], v187, v35
	v_cmp_le_i32_e64 s[16:17], v171, v35
	v_cmp_le_i32_e64 s[22:23], v188, v35
	v_cmp_le_i32_e64 s[26:27], v190, v35
	v_cmp_le_i32_e64 s[28:29], v191, v35
	v_cmp_le_i32_e64 s[24:25], v189, v35
	v_cmp_le_i32_e64 s[30:31], v192, v35
	s_waitcnt lgkmcnt(1)
	v_mfma_f32_32x32x16_bf16 v[2:17], v[36:39], v[72:75], v[2:17]
	v_cmp_le_i32_e64 s[36:37], v194, v35
	v_cmp_le_i32_e64 s[38:39], v195, v35
	v_cmp_le_i32_e64 s[34:35], v193, v35
	v_cmp_le_i32_e64 s[40:41], v196, v35
	v_cmp_le_i32_e64 s[44:45], v198, v35
	v_cmp_le_i32_e64 s[46:47], v199, v35
	v_cmp_le_i32_e64 s[42:43], v197, v35
	s_waitcnt lgkmcnt(0)
	v_mfma_f32_32x32x16_bf16 v[18:33], v[40:43], v[72:75], v[18:33]
	ds_read_b128 v[36:39], v44 offset:4096
	ds_read_b128 v[40:43], v44 offset:4608
	v_cmp_le_i32_e64 s[48:49], v200, v35
	v_cmp_le_i32_e64 s[52:53], v202, v35
	v_cmp_le_i32_e64 s[54:55], v203, v35
	v_cmp_le_i32_e64 s[50:51], v201, v35
	v_cmp_le_i32_e64 s[56:57], v204, v35
	v_cmp_le_i32_e64 s[60:61], v206, v35
	s_waitcnt lgkmcnt(1)
	v_mfma_f32_32x32x16_bf16 v[2:17], v[36:39], v[76:79], v[2:17]
	v_cmp_le_i32_e64 s[62:63], v207, v35
	v_cmp_le_i32_e64 s[58:59], v205, v35
	v_cmp_le_i32_e64 s[64:65], v208, v35
	v_cmp_le_i32_e64 s[68:69], v210, v35
	v_cmp_le_i32_e64 s[70:71], v211, v35
	v_cmp_le_i32_e64 s[66:67], v209, v35
	v_mov_b32_e32 v47, v0
	s_waitcnt lgkmcnt(0)
	v_mfma_f32_32x32x16_bf16 v[18:33], v[40:43], v[76:79], v[18:33]
	ds_read_b128 v[36:39], v44 offset:6144
	ds_read_b128 v[40:43], v44 offset:6656
	v_mov_b32_e32 v44, v142
	v_max_f32_e32 v0, v44, v44
	s_add_i32 s91, s91, -1
	s_cmp_eq_u32 s91, 0
	s_waitcnt lgkmcnt(1)
	v_mfma_f32_32x32x16_bf16 v[2:17], v[36:39], v[80:83], v[2:17]
	ds_read_b128 v[36:39], v34 offset:8192
	s_waitcnt lgkmcnt(1)
	v_mfma_f32_32x32x16_bf16 v[18:33], v[40:43], v[80:83], v[18:33]
	ds_read_b128 v[40:43], v34 offset:8704
	s_waitcnt lgkmcnt(0)
	v_add_u32_e32 v34, 0x4800, v34
	s_waitcnt lgkmcnt(1)
	v_mfma_f32_32x32x16_bf16 v[2:17], v[36:39], v[96:99], v[2:17]
	v_cndmask_b32_e32 v36, v181, v45, vcc
	v_lshlrev_b32_e32 v212, 2, v36
	v_cmp_le_i32_e32 vcc, v167, v35
	v_subrev_u32_e32 v35, 64, v35
	s_waitcnt lgkmcnt(0)
	v_mfma_f32_32x32x16_bf16 v[18:33], v[40:43], v[96:99], v[18:33]
	s_nop 5
	v_cndmask_b32_e64 v3, v180, v3, s[6:7]
	v_max_f32_e32 v37, v3, v3
	v_cndmask_b32_e32 v2, v180, v2, vcc
	v_cndmask_b32_e64 v4, v180, v4, s[14:15]
	v_cndmask_b32_e64 v5, v180, v5, s[18:19]
	v_cndmask_b32_e64 v6, v180, v6, s[22:23]
	v_cndmask_b32_e64 v7, v180, v7, s[26:27]
	v_cndmask_b32_e64 v19, v180, v19, s[8:9]
	v_max_f32_e32 v36, v19, v19
	v_cndmask_b32_e64 v18, v180, v18, s[0:1]
	v_cndmask_b32_e64 v21, v180, v21, s[20:21]
	v_max_f32_e32 v36, v37, v36
	v_cndmask_b32_e64 v20, v180, v20, s[16:17]
	v_cndmask_b32_e64 v23, v180, v23, s[28:29]
	v_max3_f32 v38, v2, v18, v4
	v_max3_f32 v36, v36, v5, v21
	v_cndmask_b32_e64 v22, v180, v22, s[24:25]
	v_cndmask_b32_e64 v8, v180, v8, s[30:31]
	v_cndmask_b32_e64 v9, v180, v9, s[36:37]
	v_cndmask_b32_e64 v25, v180, v25, s[38:39]
	v_max3_f32 v37, v38, v20, v6
	v_max3_f32 v36, v36, v7, v23
	v_cndmask_b32_e64 v24, v180, v24, s[34:35]
	v_cndmask_b32_e64 v10, v180, v10, s[40:41]
	v_cndmask_b32_e64 v11, v180, v11, s[44:45]
	v_cndmask_b32_e64 v27, v180, v27, s[46:47]
	v_max3_f32 v37, v37, v22, v8
	v_max3_f32 v36, v36, v9, v25
	v_cndmask_b32_e64 v26, v180, v26, s[42:43]
	v_cndmask_b32_e64 v12, v180, v12, s[48:49]
	v_cndmask_b32_e64 v13, v180, v13, s[52:53]
	v_cndmask_b32_e64 v29, v180, v29, s[54:55]
	v_max3_f32 v37, v37, v24, v10
	v_max3_f32 v36, v36, v11, v27
	v_cndmask_b32_e64 v28, v180, v28, s[50:51]
	v_cndmask_b32_e64 v14, v180, v14, s[56:57]
	v_cndmask_b32_e64 v15, v180, v15, s[60:61]
	v_cndmask_b32_e64 v31, v180, v31, s[62:63]
	v_max3_f32 v37, v37, v26, v12
	v_max3_f32 v36, v36, v13, v29
	v_cndmask_b32_e64 v30, v180, v30, s[58:59]
	v_cndmask_b32_e64 v16, v180, v16, s[64:65]
	v_cndmask_b32_e64 v17, v180, v17, s[68:69]
	v_cndmask_b32_e64 v33, v180, v33, s[70:71]
	v_max3_f32 v37, v37, v28, v14
	v_max3_f32 v36, v36, v15, v31
	v_cndmask_b32_e64 v32, v180, v32, s[66:67]
	v_max3_f32 v37, v37, v30, v16
	v_max3_f32 v36, v36, v17, v33
	v_max3_f32 v36, v37, v32, v36
	v_mov_b32_e32 v37, v36
	v_mov_b32_e32 v251, v36
	s_nop 1
	v_permlane32_swap_b32_e32 v37, v251
	s_waitcnt lgkmcnt(0)
; DI float ex2(float x) { return __builtin_amdgcn_exp2f(x); }
; DI void smx_stats(const f32x16& x0, const f32x16& x1, float& m, float& l) {
;     const float mn = fmaxf(m, tile_max(x0, x1) * C2);
;     l *= ex2(m - mn); m = mn;
;     float s = 0.f;
; #pragma unroll
;     for (int i = 0; i < 16; ++i) s += ex2(fmaf(x0[i], C2, -mn)) + ex2(fmaf(x1[i], C2, -mn));
;     l += s;
; }
; DI void nsa_unit(const bf16* PR, const float* AUX, const bf16* KC, const bf16* VC, bf16* MIX, char* sm, int b, int qb) {
;     ...
;         for (int it = 0; it < ntc; ++it) { const char* cb = sm + it * STG; f32x16 x0, x1; qk_tile(cb, qr, r32, hi, x0, x1); mask_tile(x0, x1, 0, khc - 64 * it, hi); smx_stats(x0, x1, m, l); }
;         const float lt = l + __shfl_xor(l, 32); const float invl = lt > 0.f ? 1.f / lt : 0.f;
;         float carry = 0.f;
; #pragma unroll
;         for (int i = 0; i < 16; ++i) { o0[i] = 0.f; o1[i] = 0.f; }
	v_max_f32_e32 v37, v37, v251
	v_max_f32_e32 v36, v36, v37
	v_mul_f32_e32 v36, 0x3e38aa3b, v36
	v_max_f32_e32 v142, v0, v36
	v_fma_f32 v0, v2, s92, -v142
	v_fma_f32 v2, v18, s92, -v142
	v_fma_f32 v3, v3, s92, -v142
	v_fma_f32 v18, v19, s92, -v142
	v_fma_f32 v19, v20, s92, -v142
	v_fma_f32 v20, v21, s92, -v142
	v_fma_f32 v21, v22, s92, -v142
	v_fma_f32 v22, v23, s92, -v142
	v_fma_f32 v23, v24, s92, -v142
	v_fma_f32 v24, v25, s92, -v142
	v_fma_f32 v25, v26, s92, -v142
	v_fma_f32 v26, v27, s92, -v142
	v_fma_f32 v27, v28, s92, -v142
	v_fma_f32 v28, v29, s92, -v142
	v_fma_f32 v29, v30, s92, -v142
	v_fma_f32 v30, v31, s92, -v142
	v_fma_f32 v31, v32, s92, -v142
	v_fma_f32 v32, v33, s92, -v142
	v_exp_f32_e32 v33, v0
	v_exp_f32_e32 v36, v2
	v_exp_f32_e32 v2, v3
	v_exp_f32_e32 v0, v18
	v_fma_f32 v4, v4, s92, -v142
	v_add_f32_e32 v3, v33, v36
	v_fma_f32 v5, v5, s92, -v142
	v_pk_add_f32 v[2:3], v[2:3], v[0:1]
	v_exp_f32_e32 v18, v4
	v_exp_f32_e32 v19, v19
	v_pk_add_f32 v[2:3], v[2:3], v[2:3] op_sel_hi:[0,1]
	v_exp_f32_e32 v4, v5
	v_exp_f32_e32 v2, v20
	v_add_f32_e32 v5, v18, v19
	v_fma_f32 v6, v6, s92, -v142
	v_fma_f32 v7, v7, s92, -v142
	v_pk_add_f32 v[2:3], v[4:5], v[2:3]
	v_exp_f32_e32 v37, v6
	v_exp_f32_e32 v21, v21
	v_pk_add_f32 v[2:3], v[2:3], v[2:3] op_sel_hi:[0,1]
	v_exp_f32_e32 v6, v7
	v_exp_f32_e32 v2, v22
	v_add_f32_e32 v7, v37, v21
	v_fma_f32 v8, v8, s92, -v142
	v_fma_f32 v9, v9, s92, -v142
	v_pk_add_f32 v[2:3], v[6:7], v[2:3]
	v_exp_f32_e32 v38, v8
	v_exp_f32_e32 v23, v23
	v_pk_add_f32 v[2:3], v[2:3], v[2:3] op_sel_hi:[0,1]
	v_exp_f32_e32 v8, v9
	v_exp_f32_e32 v2, v24
	v_add_f32_e32 v9, v38, v23
	v_fma_f32 v10, v10, s92, -v142
	v_fma_f32 v11, v11, s92, -v142
	v_pk_add_f32 v[2:3], v[8:9], v[2:3]
	v_exp_f32_e32 v0, v10
	v_exp_f32_e32 v10, v25
	v_pk_add_f32 v[2:3], v[2:3], v[2:3] op_sel_hi:[0,1]
	v_exp_f32_e32 v4, v11
	v_exp_f32_e32 v2, v26
	v_add_f32_e32 v5, v0, v10
	v_fma_f32 v12, v12, s92, -v142
	v_fma_f32 v13, v13, s92, -v142
	v_pk_add_f32 v[2:3], v[4:5], v[2:3]
	v_exp_f32_e32 v11, v12
	v_exp_f32_e32 v7, v27
	v_pk_add_f32 v[2:3], v[2:3], v[2:3] op_sel_hi:[0,1]
	v_exp_f32_e32 v6, v13
	v_exp_f32_e32 v2, v28
	v_add_f32_e32 v7, v11, v7
	v_fma_f32 v14, v14, s92, -v142
	v_fma_f32 v15, v15, s92, -v142
	v_pk_add_f32 v[2:3], v[6:7], v[2:3]
	v_exp_f32_e32 v8, v14
	v_exp_f32_e32 v9, v29
	v_pk_add_f32 v[2:3], v[2:3], v[2:3] op_sel_hi:[0,1]
	v_exp_f32_e32 v4, v15
	v_exp_f32_e32 v2, v30
	v_add_f32_e32 v5, v8, v9
	v_fma_f32 v16, v16, s92, -v142
	v_fma_f32 v17, v17, s92, -v142
	v_pk_add_f32 v[2:3], v[4:5], v[2:3]
	v_exp_f32_e32 v0, v16
	v_exp_f32_e32 v7, v31
	v_pk_add_f32 v[2:3], v[2:3], v[2:3] op_sel_hi:[0,1]
	v_exp_f32_e32 v6, v17
	v_exp_f32_e32 v2, v32
	v_sub_f32_e32 v4, v44, v142
	v_exp_f32_e32 v4, v4
	v_add_f32_e32 v7, v0, v7
	v_pk_add_f32 v[2:3], v[6:7], v[2:3]
	s_nop 0
	v_add_f32_e32 v0, v2, v3
	v_fmac_f32_e32 v0, v47, v4
	s_cbranch_scc0 .LBB0_488
	ds_bpermute_b32 v2, v212, v0
	v_lshlrev_b32_e32 v215, 4, v149
	v_lshlrev_b32_e32 v4, 1, v149
	v_lshlrev_b32_e32 v214, 8, v160
	v_and_b32_e32 v216, 0xc0, v215
	s_waitcnt lgkmcnt(0)
	v_add_f32_e32 v0, v0, v2
	v_div_scale_f32 v2, s[0:1], v0, v0, 1.0
	v_rcp_f32_e32 v3, v2
	v_div_scale_f32 v5, vcc, 1.0, v0, 1.0
	s_add_i32 s0, s72, s81
	v_fma_f32 v6, -v2, v3, 1.0
	v_fmac_f32_e32 v3, v6, v3
	v_mul_f32_e32 v6, v5, v3
	v_fma_f32 v7, -v2, v6, v5
	v_fmac_f32_e32 v6, v7, v3
	v_fma_f32 v2, -v2, v6, v5
	v_div_fmas_f32 v2, v2, v3, v6
	v_div_fixup_f32 v2, v2, v0, 1.0
	v_cmp_lt_f32_e32 vcc, 0, v0
	v_add_u32_e32 v0, s0, v135
	s_movk_i32 s0, 0x84
	v_mov_b32_e32 v158, 0
	v_cndmask_b32_e32 v66, 0, v2, vcc
	v_and_b32_e32 v213, 32, v4
	v_mul_lo_u32 v0, v0, s0
	s_mov_b32 s0, 0xb000
	v_or_b32_e32 v2, v214, v216
	v_mov_b32_e32 v67, v66
	v_add3_u32 v0, v0, v167, s0
	v_or3_b32 v143, v2, v213, v163
	v_or_b32_e32 v145, 0x2000, v165
	v_add_u32_e32 v146, v166, v165
	v_mov_b32_e32 v2, 0
	v_mov_b32_e32 v3, v158
	v_mov_b32_e32 v4, v158
	v_mov_b32_e32 v5, v158
	v_mov_b32_e32 v6, v158
	v_mov_b32_e32 v7, v158
	v_mov_b32_e32 v8, v158
	v_mov_b32_e32 v9, v158
	v_mov_b32_e32 v10, v158
	v_mov_b32_e32 v11, v158
	v_mov_b32_e32 v12, v158
	v_mov_b32_e32 v13, v158
	v_mov_b32_e32 v14, v158
	v_mov_b32_e32 v15, v158
	v_mov_b32_e32 v16, v158
	v_mov_b32_e32 v17, v158
	v_mov_b32_e32 v18, 0
	v_mov_b32_e32 v19, v158
	v_mov_b32_e32 v20, v158
	v_mov_b32_e32 v21, v158
	v_mov_b32_e32 v22, v158
	v_mov_b32_e32 v23, v158
	v_mov_b32_e32 v24, v158
	v_mov_b32_e32 v25, v158
	v_mov_b32_e32 v26, v158
	v_mov_b32_e32 v27, v158
	v_mov_b32_e32 v28, v158
	v_mov_b32_e32 v29, v158
	v_mov_b32_e32 v30, v158
	v_mov_b32_e32 v31, v158
	v_mov_b32_e32 v32, v158
	v_mov_b32_e32 v33, v158

; DI float ex2(float x) { return __builtin_amdgcn_exp2f(x); }
; DI void smx_tile_sel(f32x16& x0, f32x16& x1, float& m, float& l, f32x16& o0, f32x16& o1, bool sel) {
;     const float tm = tile_max(x0, x1) * C2;
;     const float mn = sel ? fmaxf(m, tm) : m;
;     const float al = ex2(m - mn); m = mn; l *= al;
;     if (__any(al != 1.f)) {
; #pragma unroll
;         for (int i = 0; i < 16; ++i) { o0[i] *= al; o1[i] *= al; }
;     }
.LBB0_522:
	v_max_f32_e32 v0, v37, v37
	v_max_f32_e32 v2, v53, v53
	v_max_f32_e32 v0, v2, v0
	v_max3_f32 v2, v52, v36, v54
	v_max3_f32 v0, v0, v55, v39
	v_max3_f32 v2, v2, v38, v56
	v_max3_f32 v0, v0, v57, v41
	v_max3_f32 v2, v2, v40, v58
	v_max3_f32 v0, v0, v59, v43
	v_max3_f32 v2, v2, v42, v60
	v_max3_f32 v0, v0, v61, v45
	v_max3_f32 v2, v2, v44, v62
	v_max3_f32 v0, v0, v63, v47
	v_max3_f32 v2, v2, v46, v64
	v_max3_f32 v0, v0, v65, v49
	v_max3_f32 v2, v2, v48, v66
	v_max3_f32 v0, v0, v67, v51
	v_max3_f32 v0, v2, v50, v0
	v_mov_b32_e32 v2, v0
	v_mov_b32_e32 v251, v0
	s_nop 1
	v_permlane32_swap_b32_e32 v2, v251
	s_or_b64 s[4:5], s[4:5], vcc
	s_waitcnt lgkmcnt(0)
	v_max_f32_e32 v2, v2, v251
	v_max_f32_e32 v0, v0, v2
	v_mul_f32_e32 v0, 0x3e38aa3b, v0
	v_max_f32_e32 v2, v146, v146
	v_max_f32_e32 v0, v2, v0
	v_cndmask_b32_e64 v3, v146, v0, s[4:5]
	v_sub_f32_e32 v2, v146, v3
	v_exp_f32_e32 v2, v2
	s_nop 0
	v_cmp_neq_f32_e32 vcc, 1.0, v2
	s_cbranch_vccz .LBB0_524
	v_pk_mul_f32 v[34:35], v[34:35], v[2:3] op_sel_hi:[1,0]
	v_pk_mul_f32 v[32:33], v[32:33], v[2:3] op_sel_hi:[1,0]
	v_pk_mul_f32 v[30:31], v[30:31], v[2:3] op_sel_hi:[1,0]
	v_pk_mul_f32 v[28:29], v[28:29], v[2:3] op_sel_hi:[1,0]
	v_pk_mul_f32 v[26:27], v[26:27], v[2:3] op_sel_hi:[1,0]
	v_pk_mul_f32 v[24:25], v[24:25], v[2:3] op_sel_hi:[1,0]
	v_pk_mul_f32 v[22:23], v[22:23], v[2:3] op_sel_hi:[1,0]
	v_pk_mul_f32 v[20:21], v[20:21], v[2:3] op_sel_hi:[1,0]
	v_pk_mul_f32 v[18:19], v[18:19], v[2:3] op_sel_hi:[1,0]
	v_pk_mul_f32 v[16:17], v[16:17], v[2:3] op_sel_hi:[1,0]
	v_pk_mul_f32 v[14:15], v[14:15], v[2:3] op_sel_hi:[1,0]
	v_pk_mul_f32 v[12:13], v[12:13], v[2:3] op_sel_hi:[1,0]
	v_pk_mul_f32 v[10:11], v[10:11], v[2:3] op_sel_hi:[1,0]
	v_pk_mul_f32 v[8:9], v[8:9], v[2:3] op_sel_hi:[1,0]
	v_pk_mul_f32 v[6:7], v[6:7], v[2:3] op_sel_hi:[1,0]
	v_pk_mul_f32 v[4:5], v[4:5], v[2:3] op_sel_hi:[1,0]

; DI float ex2(float x) { return __builtin_amdgcn_exp2f(x); }
; DI float tile_max(const f32x16& x0, const f32x16& x1) {
;     float ma = __builtin_fmaxf(x0[0], x1[0]), mb = __builtin_fmaxf(x0[1], x1[1]);
; #pragma unroll
;     for (int i = 2; i < 16; i += 2) { ma = __builtin_fmaxf(__builtin_fmaxf(ma, x0[i]), x1[i]); mb = __builtin_fmaxf(__builtin_fmaxf(mb, x0[i + 1]), x1[i + 1]); }
;     const float mx = __builtin_fmaxf(ma, mb);
;     return __builtin_fmaxf(mx, __shfl_xor(mx, 32));
; }
; DI void smx_tile(f32x16& x0, f32x16& x1, float& m, float& l, f32x16& o0, f32x16& o1) {
;     const float mn = fmaxf(m, tile_max(x0, x1) * C2);
;     const float al = ex2(m - mn); m = mn; l *= al;
;     if (__any(al != 1.f)) {
; #pragma unroll
;         for (int i = 0; i < 16; ++i) { o0[i] *= al; o1[i] *= al; }
.LBB0_539:
	v_max_f32_e32 v0, v37, v37
	v_max_f32_e32 v2, v53, v53
	v_max_f32_e32 v0, v2, v0
	v_max3_f32 v2, v52, v36, v54
	v_max3_f32 v0, v0, v55, v39
	v_max3_f32 v2, v2, v38, v56
	v_max3_f32 v0, v0, v57, v41
	v_max3_f32 v2, v2, v40, v58
	v_max3_f32 v0, v0, v59, v43
	v_max3_f32 v2, v2, v42, v60
	v_max3_f32 v0, v0, v61, v45
	v_max3_f32 v2, v2, v44, v62
	v_max3_f32 v0, v0, v63, v47
	v_max3_f32 v2, v2, v46, v64
	v_max3_f32 v0, v0, v65, v49
	v_max3_f32 v2, v2, v48, v66
	v_max3_f32 v0, v0, v67, v51
	v_max3_f32 v0, v2, v50, v0
	v_mov_b32_e32 v2, v0
	v_mov_b32_e32 v251, v0
	s_nop 1
	v_permlane32_swap_b32_e32 v2, v251
	s_waitcnt lgkmcnt(0)
	v_max_f32_e32 v2, v2, v251
	v_max_f32_e32 v0, v0, v2
	v_mul_f32_e32 v0, 0x3e38aa3b, v0
	v_max_f32_e32 v2, v224, v224
	v_max_f32_e32 v3, v2, v0
	v_sub_f32_e32 v0, v224, v3
	v_exp_f32_e32 v2, v0
	s_nop 0
	v_cmp_neq_f32_e32 vcc, 1.0, v2
	s_cbranch_vccz .LBB0_541
	v_pk_mul_f32 v[34:35], v[34:35], v[2:3] op_sel_hi:[1,0]
	v_pk_mul_f32 v[32:33], v[32:33], v[2:3] op_sel_hi:[1,0]
	v_pk_mul_f32 v[30:31], v[30:31], v[2:3] op_sel_hi:[1,0]
	v_pk_mul_f32 v[28:29], v[28:29], v[2:3] op_sel_hi:[1,0]
	v_pk_mul_f32 v[26:27], v[26:27], v[2:3] op_sel_hi:[1,0]
	v_pk_mul_f32 v[24:25], v[24:25], v[2:3] op_sel_hi:[1,0]
	v_pk_mul_f32 v[22:23], v[22:23], v[2:3] op_sel_hi:[1,0]
	v_pk_mul_f32 v[20:21], v[20:21], v[2:3] op_sel_hi:[1,0]
	v_pk_mul_f32 v[18:19], v[18:19], v[2:3] op_sel_hi:[1,0]
	v_pk_mul_f32 v[16:17], v[16:17], v[2:3] op_sel_hi:[1,0]
	v_pk_mul_f32 v[14:15], v[14:15], v[2:3] op_sel_hi:[1,0]
	v_pk_mul_f32 v[12:13], v[12:13], v[2:3] op_sel_hi:[1,0]
	v_pk_mul_f32 v[10:11], v[10:11], v[2:3] op_sel_hi:[1,0]
	v_pk_mul_f32 v[8:9], v[8:9], v[2:3] op_sel_hi:[1,0]
	v_pk_mul_f32 v[6:7], v[6:7], v[2:3] op_sel_hi:[1,0]
	v_pk_mul_f32 v[4:5], v[4:5], v[2:3] op_sel_hi:[1,0]
